# MLA MFMA block: one address computation shared by the two K-fragment reads of a k-step (7 fewer VALU ops per block in the critical MFMA wave)
# speedup vs baseline: 1.0039x; 1.0039x over previous
.LBB0_666:
	s_barrier
	s_setprio 3
	s_mov_b32 s12, s94
	s_mov_b32 s94, s8
	v_add_u32_e32 v250, s94, v185
	ds_read_b64_tr_b16 v[202:203], v250 offset:0
	ds_read_b64_tr_b16 v[204:205], v250 offset:0x800
	ds_read_b64_tr_b16 v[206:207], v250 offset:0x1000
	ds_read_b64_tr_b16 v[208:209], v250 offset:0x1800
	ds_read_b64_tr_b16 v[210:211], v250 offset:0x2000
	ds_read_b64_tr_b16 v[212:213], v250 offset:0x2800
	ds_read_b64_tr_b16 v[214:215], v250 offset:0x3000
	ds_read_b64_tr_b16 v[216:217], v250 offset:0x3800
	ds_read_b128 v[66:69], v189 offset:16384
	ds_read_b128 v[70:73], v189 offset:24576
	s_waitcnt lgkmcnt(8)
	v_mfma_f32_32x32x16_bf16 v[50:65], v[130:133], v[202:205], v[50:65]
	ds_read_b64_tr_b16 v[218:219], v250 offset:0x200
	ds_read_b64_tr_b16 v[220:221], v250 offset:0xa00
	s_waitcnt lgkmcnt(8)
	v_mfma_f32_32x32x16_bf16 v[50:65], v[126:129], v[206:209], v[50:65]
	ds_read_b64_tr_b16 v[222:223], v250 offset:0x1200
	ds_read_b64_tr_b16 v[224:225], v250 offset:0x1a00
	ds_read_b128 v[194:197], v190 offset:16384
	s_waitcnt lgkmcnt(9)
	v_mfma_f32_32x32x16_bf16 v[50:65], v[122:125], v[210:213], v[50:65]
	ds_read_b64_tr_b16 v[226:227], v250 offset:0x2200
	ds_read_b64_tr_b16 v[228:229], v250 offset:0x2a00
	s_waitcnt lgkmcnt(9)
	v_mfma_f32_32x32x16_bf16 v[50:65], v[118:121], v[214:217], v[50:65]
	ds_read_b64_tr_b16 v[230:231], v250 offset:0x3200
	ds_read_b64_tr_b16 v[232:233], v250 offset:0x3a00
	ds_read_b128 v[198:201], v190 offset:24576
	s_waitcnt lgkmcnt(8)
	v_mfma_f32_32x32x16_bf16 v[34:49], v[130:133], v[218:221], v[34:49]
	ds_read_b64_tr_b16 v[202:203], v250 offset:0x400
	ds_read_b64_tr_b16 v[204:205], v250 offset:0xc00
	s_waitcnt lgkmcnt(8)
	v_mfma_f32_32x32x16_bf16 v[34:49], v[126:129], v[222:225], v[34:49]
	ds_read_b64_tr_b16 v[206:207], v250 offset:0x1400
	ds_read_b64_tr_b16 v[208:209], v250 offset:0x1c00
	ds_read_b128 v[234:237], v191 offset:16384
	s_waitcnt lgkmcnt(8)
	v_mfma_f32_32x32x16_bf16 v[34:49], v[122:125], v[226:229], v[34:49]
	ds_read_b64_tr_b16 v[210:211], v250 offset:0x2400
	ds_read_b64_tr_b16 v[212:213], v250 offset:0x2c00
	s_waitcnt lgkmcnt(8)
	v_mfma_f32_32x32x16_bf16 v[34:49], v[118:121], v[230:233], v[34:49]
	ds_read_b64_tr_b16 v[214:215], v250 offset:0x3400
	ds_read_b64_tr_b16 v[216:217], v250 offset:0x3c00
	ds_read_b128 v[238:241], v191 offset:24576
	s_waitcnt lgkmcnt(8)
	v_mfma_f32_32x32x16_bf16 v[18:33], v[130:133], v[202:205], v[18:33]
	ds_read_b64_tr_b16 v[218:219], v250 offset:0x600
	ds_read_b64_tr_b16 v[220:221], v250 offset:0xe00
	s_waitcnt lgkmcnt(8)
	v_mfma_f32_32x32x16_bf16 v[18:33], v[126:129], v[206:209], v[18:33]
	ds_read_b64_tr_b16 v[222:223], v250 offset:0x1600
	ds_read_b64_tr_b16 v[224:225], v250 offset:0x1e00
	ds_read_b128 v[242:245], v192 offset:16384
	s_waitcnt lgkmcnt(8)
	v_mfma_f32_32x32x16_bf16 v[18:33], v[122:125], v[210:213], v[18:33]
	ds_read_b64_tr_b16 v[226:227], v250 offset:0x2600
	ds_read_b64_tr_b16 v[228:229], v250 offset:0x2e00
	s_waitcnt lgkmcnt(8)
	v_mfma_f32_32x32x16_bf16 v[18:33], v[118:121], v[214:217], v[18:33]
	ds_read_b64_tr_b16 v[230:231], v250 offset:0x3600
	ds_read_b64_tr_b16 v[232:233], v250 offset:0x3e00
	ds_read_b128 v[246:249], v192 offset:24576
	s_waitcnt lgkmcnt(8)
	v_mfma_f32_32x32x16_bf16 v[2:17], v[130:133], v[218:221], v[2:17]
	s_waitcnt lgkmcnt(6)
	v_mfma_f32_32x32x16_bf16 v[2:17], v[126:129], v[222:225], v[2:17]
	v_add_u32_e32 v206, v187, v168
	ds_read_b128 v[202:205], v206 offset:16384
	ds_read_b128 v[206:209], v206 offset:24576
	s_waitcnt lgkmcnt(5)
	v_mfma_f32_32x32x16_bf16 v[2:17], v[122:125], v[226:229], v[2:17]
	s_waitcnt lgkmcnt(3)
	v_mfma_f32_32x32x16_bf16 v[2:17], v[118:121], v[230:233], v[2:17]
	v_add_u32_e32 v214, v187, v170
	ds_read_b128 v[210:213], v214 offset:16384
	ds_read_b128 v[214:217], v214 offset:24576
	v_mfma_f32_32x32x16_bf16 v[82:97], v[66:69], v[114:117], 0
	v_mfma_f32_32x32x16_bf16 v[66:81], v[70:73], v[114:117], 0
	ds_read_b128 v[218:221], v159
	v_add_u32_e32 v226, v187, v172
	ds_read_b128 v[222:225], v226 offset:16384
	ds_read_b128 v[226:229], v226 offset:24576
	v_mfma_f32_32x32x16_bf16 v[82:97], v[194:197], v[110:113], v[82:97]
	v_mfma_f32_32x32x16_bf16 v[66:81], v[198:201], v[110:113], v[66:81]
	ds_read_b128 v[230:233], v159 offset:1024
	v_add_u32_e32 v198, v187, v174
	ds_read_b128 v[194:197], v198 offset:16384
	ds_read_b128 v[198:201], v198 offset:24576
	v_mfma_f32_32x32x16_bf16 v[82:97], v[234:237], v[106:109], v[82:97]
	v_mfma_f32_32x32x16_bf16 v[66:81], v[238:241], v[106:109], v[66:81]
	ds_read_b128 v[234:237], v159 offset:2048
	v_add_u32_e32 v238, v188, v177
	ds_read_b128 v[238:241], v238 offset:40960
	v_mfma_f32_32x32x16_bf16 v[82:97], v[242:245], v[102:105], v[82:97]
	s_waitcnt lgkmcnt(12)
	v_mfma_f32_32x32x16_bf16 v[66:81], v[246:249], v[102:105], v[66:81]
	v_add_u32_e32 v242, v188, v177
	ds_read_b128 v[242:245], v242 offset:45056
	ds_read_b128 v[246:249], v159 offset:3072
	s_waitcnt lgkmcnt(13)
	v_mfma_f32_32x32x16_bf16 v[82:97], v[202:205], v[98:101], v[82:97]
	s_waitcnt lgkmcnt(12)
	v_mfma_f32_32x32x16_bf16 v[66:81], v[206:209], v[98:101], v[66:81]
	v_add_u32_e32 v206, v188, v179
	ds_read_b128 v[202:205], v206 offset:40960
	ds_read_b128 v[206:209], v206 offset:45056
	s_waitcnt lgkmcnt(11)
	v_mfma_f32_32x32x16_bf16 v[82:97], v[210:213], v[218:221], v[82:97]
	v_mfma_f32_32x32x16_bf16 v[66:81], v[214:217], v[218:221], v[66:81]
	ds_read_b128 v[210:213], v159 offset:4096
	v_add_u32_e32 v218, v188, v181
	ds_read_b128 v[214:217], v218 offset:40960
	ds_read_b128 v[218:221], v218 offset:45056
	s_waitcnt lgkmcnt(11)
	v_mfma_f32_32x32x16_bf16 v[82:97], v[222:225], v[230:233], v[82:97]
	v_mfma_f32_32x32x16_bf16 v[66:81], v[226:229], v[230:233], v[66:81]
	ds_read_b128 v[222:225], v159 offset:5120
	v_add_u32_e32 v230, v188, v183
	ds_read_b128 v[226:229], v230 offset:40960
	ds_read_b128 v[230:233], v230 offset:45056
	s_waitcnt lgkmcnt(11)
	v_mfma_f32_32x32x16_bf16 v[82:97], v[194:197], v[234:237], v[82:97]
	v_mfma_f32_32x32x16_bf16 v[66:81], v[198:201], v[234:237], v[66:81]
	ds_read_b128 v[194:197], v159 offset:6144
	s_waitcnt lgkmcnt(9)
	v_mfma_f32_32x32x16_bf16 v[82:97], v[238:241], v[246:249], v[82:97]
	v_mfma_f32_32x32x16_bf16 v[66:81], v[242:245], v[246:249], v[66:81]
	s_waitcnt lgkmcnt(6)
	v_mfma_f32_32x32x16_bf16 v[82:97], v[202:205], v[210:213], v[82:97]
	v_mfma_f32_32x32x16_bf16 v[66:81], v[206:209], v[210:213], v[66:81]
	s_waitcnt lgkmcnt(3)
	v_mfma_f32_32x32x16_bf16 v[82:97], v[214:217], v[222:225], v[82:97]
	v_mfma_f32_32x32x16_bf16 v[66:81], v[218:221], v[222:225], v[66:81]
	s_waitcnt lgkmcnt(0)
	v_mfma_f32_32x32x16_bf16 v[82:97], v[226:229], v[194:197], v[82:97]
	v_mfma_f32_32x32x16_bf16 v[66:81], v[230:233], v[194:197], v[66:81]
	s_and_b64 vcc, exec, s[6:7]
	s_cbranch_vccnz .LBB0_668
	s_waitcnt vmcnt(0)
